# v11 plus partial hosting shift: layer 1 FFN1 gate/up int8 quantisation moved from the prologue to the converter workgroups of layer 0 w_in phase
# baseline (speedup 1.0000x reference)
.LBB0_26:
	s_or_b64 exec, exec, s[4:5]
	s_add_i32 s4, 0, 0x20800
	s_waitcnt lgkmcnt(0)
	s_barrier
	v_mov_b32_e32 v2, s4
	ds_read_b32 v2, v2
	s_movk_i32 s5, 0x2ff
	s_movk_i32 s4, 0x300
	s_waitcnt lgkmcnt(0)
	v_cmp_lt_i32_e32 vcc, s5, v2
	v_readfirstlane_b32 s27, v2
	v_cmp_gt_i32_e64 s[4:5], s4, v2
	s_cbranch_vccnz .LBB0_36
	s_cmpk_lt_i32 s27, 0x2c0
	s_cselect_b32 s22, 0, 0x2c0
	s_add_i32 s22, s22, s27
	s_cmpk_lt_i32 s22, 0x580
	s_mul_hi_i32 s18, s22, 0x2e8ba2e9
	s_cselect_b64 s[8:9], -1, 0
	s_lshr_b32 s19, s18, 31
	s_ashr_i32 s26, s18, 5
	s_add_i32 s26, s26, s19
	s_and_b64 vcc, exec, s[8:9]
	s_cbranch_vccz .LBB0_29
	s_mul_i32 s18, s26, 0xb0
	s_sub_i32 s23, s22, s18
	s_movk_i32 s21, 0x1600
	s_cbranch_execz .LBB0_30
	s_branch .LBB0_31

.LBB0_36:
	s_andn2_b64 vcc, exec, s[4:5]
	s_cbranch_vccnz .LBB0_75
	v_ashrrev_i32_e32 v134, 3, v70
	v_add_u32_e32 v71, 64, v134
	v_lshlrev_b32_e32 v72, 6, v71
	v_ashrrev_i32_e32 v71, 1, v71
	v_and_b32_e32 v71, 0xffffffc0, v71
	v_add3_u32 v71, 0, v72, v71
	v_add_u32_e32 v72, 0x80, v134
	v_lshlrev_b32_e32 v73, 6, v72
	v_ashrrev_i32_e32 v72, 1, v72
	v_and_b32_e32 v72, 0xffffffc0, v72
	v_add3_u32 v72, 0, v73, v72
	v_add_u32_e32 v73, 0xc0, v134
	v_lshlrev_b32_e32 v74, 6, v73
	v_ashrrev_i32_e32 v73, 1, v73
	v_and_b32_e32 v73, 0xffffffc0, v73
	v_add3_u32 v73, 0, v74, v73
	v_add_u32_e32 v74, 0x100, v134
	v_lshlrev_b32_e32 v75, 6, v74
	v_ashrrev_i32_e32 v74, 1, v74
	v_and_b32_e32 v74, 0xffffffc0, v74
	v_add3_u32 v74, 0, v75, v74
	v_add_u32_e32 v75, 0x140, v134
	v_lshlrev_b32_e32 v76, 6, v75
	v_ashrrev_i32_e32 v75, 1, v75
	v_and_b32_e32 v75, 0xffffffc0, v75
	v_add3_u32 v75, 0, v76, v75
	v_add_u32_e32 v76, 0x180, v134
	v_lshlrev_b32_e32 v77, 6, v76
	v_ashrrev_i32_e32 v76, 1, v76
	v_and_b32_e32 v76, 0xffffffc0, v76
	v_add3_u32 v76, 0, v77, v76
	v_add_u32_e32 v77, 0x1c0, v134
	v_lshlrev_b32_e32 v78, 6, v77
	v_ashrrev_i32_e32 v77, 1, v77
	v_and_b32_e32 v77, 0xffffffc0, v77
	v_add3_u32 v77, 0, v78, v77
	v_add_u32_e32 v78, 0x200, v134
	v_lshlrev_b32_e32 v79, 6, v78
	v_ashrrev_i32_e32 v78, 1, v78
	v_and_b32_e32 v78, 0xffffffc0, v78
	v_add3_u32 v78, 0, v79, v78
	v_add_u32_e32 v79, 0x240, v134
	v_lshlrev_b32_e32 v80, 6, v79
	v_ashrrev_i32_e32 v79, 1, v79
	v_and_b32_e32 v79, 0xffffffc0, v79
	v_add3_u32 v79, 0, v80, v79
	v_add_u32_e32 v80, 0x280, v134
	v_lshlrev_b32_e32 v81, 6, v80
	v_ashrrev_i32_e32 v80, 1, v80
	v_and_b32_e32 v80, 0xffffffc0, v80
	v_add3_u32 v80, 0, v81, v80
	v_add_u32_e32 v81, 0x2c0, v134
	v_lshlrev_b32_e32 v82, 6, v81
	v_ashrrev_i32_e32 v81, 1, v81
	v_and_b32_e32 v81, 0xffffffc0, v81
	v_add3_u32 v81, 0, v82, v81
	v_add_u32_e32 v82, 0x300, v134
	v_lshlrev_b32_e32 v83, 6, v82
	v_ashrrev_i32_e32 v82, 1, v82
	v_and_b32_e32 v82, 0xffffffc0, v82
	v_add3_u32 v82, 0, v83, v82
	v_add_u32_e32 v83, 0x340, v134
	v_lshlrev_b32_e32 v84, 6, v83
	v_ashrrev_i32_e32 v83, 1, v83
	v_and_b32_e32 v83, 0xffffffc0, v83
	v_add3_u32 v83, 0, v84, v83
	v_add_u32_e32 v84, 0x380, v134
	v_lshlrev_b32_e32 v85, 6, v84
	v_ashrrev_i32_e32 v84, 1, v84
	v_and_b32_e32 v84, 0xffffffc0, v84
	v_add3_u32 v84, 0, v85, v84
	v_add_u32_e32 v85, 0x3c0, v134
	v_lshlrev_b32_e32 v86, 6, v85
	v_ashrrev_i32_e32 v85, 1, v85
	v_and_b32_e32 v85, 0xffffffc0, v85
	v_add3_u32 v85, 0, v86, v85
	v_add_u32_e32 v86, 0x400, v134
	v_lshlrev_b32_e32 v87, 6, v86
	v_ashrrev_i32_e32 v86, 1, v86
	v_and_b32_e32 v86, 0xffffffc0, v86
	v_add3_u32 v86, 0, v87, v86
	v_add_u32_e32 v87, 0x440, v134
	v_lshlrev_b32_e32 v88, 6, v87
	v_ashrrev_i32_e32 v87, 1, v87
	v_and_b32_e32 v87, 0xffffffc0, v87
	v_add3_u32 v87, 0, v88, v87
	v_add_u32_e32 v88, 0x480, v134
	v_lshlrev_b32_e32 v89, 6, v88
	v_ashrrev_i32_e32 v88, 1, v88
	v_and_b32_e32 v88, 0xffffffc0, v88
	v_add3_u32 v88, 0, v89, v88
	v_add_u32_e32 v89, 0x4c0, v134
	v_lshlrev_b32_e32 v90, 6, v89
	v_ashrrev_i32_e32 v89, 1, v89
	v_and_b32_e32 v89, 0xffffffc0, v89
	v_add3_u32 v89, 0, v90, v89
	v_add_u32_e32 v90, 0x500, v134
	v_lshlrev_b32_e32 v91, 6, v90
	v_ashrrev_i32_e32 v90, 1, v90
	v_and_b32_e32 v90, 0xffffffc0, v90
	v_add3_u32 v90, 0, v91, v90
	v_add_u32_e32 v91, 0x540, v134
	v_lshlrev_b32_e32 v92, 6, v91
	v_ashrrev_i32_e32 v91, 1, v91
	v_and_b32_e32 v91, 0xffffffc0, v91
	v_add3_u32 v91, 0, v92, v91
	v_add_u32_e32 v92, 0x580, v134
	v_lshlrev_b32_e32 v93, 6, v92
	v_ashrrev_i32_e32 v92, 1, v92
	v_and_b32_e32 v92, 0xffffffc0, v92
	v_add3_u32 v92, 0, v93, v92
	v_add_u32_e32 v93, 0x5c0, v134
	v_lshlrev_b32_e32 v94, 6, v93
	v_ashrrev_i32_e32 v93, 1, v93
	v_and_b32_e32 v93, 0xffffffc0, v93
	v_add3_u32 v93, 0, v94, v93
	v_add_u32_e32 v94, 0x600, v134
	v_lshlrev_b32_e32 v95, 6, v94
	v_ashrrev_i32_e32 v94, 1, v94
	v_and_b32_e32 v94, 0xffffffc0, v94
	v_add3_u32 v94, 0, v95, v94
	v_add_u32_e32 v95, 0x640, v134
	v_lshlrev_b32_e32 v96, 6, v95
	v_ashrrev_i32_e32 v95, 1, v95
	v_and_b32_e32 v95, 0xffffffc0, v95
	v_add3_u32 v95, 0, v96, v95
	v_add_u32_e32 v96, 0x680, v134
	v_lshlrev_b32_e32 v97, 6, v96
	v_ashrrev_i32_e32 v96, 1, v96
	v_and_b32_e32 v96, 0xffffffc0, v96
	v_add3_u32 v96, 0, v97, v96
	v_add_u32_e32 v97, 0x6c0, v134
	v_lshlrev_b32_e32 v98, 6, v97
	v_ashrrev_i32_e32 v97, 1, v97
	v_and_b32_e32 v97, 0xffffffc0, v97
	v_add3_u32 v97, 0, v98, v97
	v_add_u32_e32 v98, 0x700, v134
	v_lshlrev_b32_e32 v99, 6, v98
	v_ashrrev_i32_e32 v98, 1, v98
	v_and_b32_e32 v98, 0xffffffc0, v98
	s_lshl_b32 s4, s20, 2
	v_add3_u32 v98, 0, v99, v98
	v_add_u32_e32 v99, 0x740, v134
	s_andn2_b32 s4, s4, 63
	v_lshlrev_b32_e32 v100, 6, v99
	v_ashrrev_i32_e32 v99, 1, v99
	s_lshl_b32 s8, s20, 7
	s_add_i32 s9, 0, 0x20400
	s_add_i32 s4, s4, 0
	v_and_b32_e32 v99, 0xffffffc0, v99
	s_add_i32 s8, s9, s8
	v_add3_u32 v99, 0, v100, v99
	v_add_u32_e32 v100, 0x780, v134
	s_add_u32 s34, s6, 0x800000
	v_lshlrev_b32_e32 v101, 6, v100
	v_ashrrev_i32_e32 v100, 1, v100
	s_addc_u32 s35, s7, 0
	v_and_b32_e32 v100, 0xffffffc0, v100
	s_add_u32 s36, s6, 0x32200000
	v_add3_u32 v100, 0, v101, v100
	v_add_u32_e32 v101, 0x7c0, v134
	s_addc_u32 s37, s7, 0
	v_lshlrev_b32_e32 v102, 6, v101
	v_ashrrev_i32_e32 v101, 1, v101
	s_add_u32 s38, s6, 0x720000
	v_and_b32_e32 v135, 28, v68
	v_lshl_add_u32 v68, v134, 6, s4
	v_and_b32_e32 v101, 0xffffffc0, v101
	v_cmp_gt_u32_e64 s[4:5], 8, v69
	v_and_b32_e32 v1, 31, v1
	v_ashrrev_i32_e32 v69, 5, v70
	s_addc_u32 s39, s7, 0
	v_and_b32_e32 v67, 56, v67
	v_add3_u32 v101, 0, v102, v101
	s_add_u32 s40, s6, 0x780000
	v_lshlrev_b32_e32 v102, 7, v69
	v_lshl_add_u32 v103, v69, 13, 0
	v_lshlrev_b32_e32 v69, 6, v69
	v_lshlrev_b32_e32 v104, 1, v1
	v_add_u32_e32 v170, s8, v66
	v_mbcnt_lo_u32_b32 v66, -1, 0
	s_mov_b32 s19, 0
	v_lshl_add_u32 v136, v1, 2, s9
	s_addc_u32 s41, s7, 0
	v_add3_u32 v137, v103, v69, v104
	v_ashrrev_i32_e32 v131, 31, v102
	v_cmp_gt_u32_e64 s[6:7], 32, v70
	v_or_b32_e32 v130, 16, v102
	v_mov_b32_e32 v133, 0
	v_add_u32_e32 v138, v68, v67
	v_add_u32_e32 v139, v71, v67
	v_add_u32_e32 v140, v72, v67
	v_add_u32_e32 v141, v73, v67
	v_add_u32_e32 v142, v74, v67
	v_add_u32_e32 v143, v75, v67
	v_add_u32_e32 v144, v76, v67
	v_add_u32_e32 v145, v77, v67
	v_add_u32_e32 v146, v78, v67
	v_add_u32_e32 v147, v79, v67
	v_add_u32_e32 v148, v80, v67
	v_add_u32_e32 v149, v81, v67
	v_add_u32_e32 v150, v82, v67
	v_add_u32_e32 v151, v83, v67
	v_add_u32_e32 v152, v84, v67
	v_add_u32_e32 v153, v85, v67
	s_add_i32 s42, 0, 0x20800
	v_add_u32_e32 v154, v86, v67
	v_add_u32_e32 v155, v87, v67
	v_add_u32_e32 v156, v88, v67
	v_add_u32_e32 v157, v89, v67
	v_add_u32_e32 v158, v90, v67
	v_add_u32_e32 v159, v91, v67
	v_add_u32_e32 v160, v92, v67
	v_add_u32_e32 v161, v93, v67
	v_add_u32_e32 v162, v94, v67
	v_add_u32_e32 v163, v95, v67
	v_add_u32_e32 v164, v96, v67
	v_add_u32_e32 v165, v97, v67
	v_add_u32_e32 v166, v98, v67
	v_add_u32_e32 v167, v99, v67
	v_add_u32_e32 v168, v100, v67
	v_add_u32_e32 v169, v101, v67
	s_movk_i32 s43, 0x2ff
	s_mov_b32 s44, 0x42fe0000
	s_mov_b32 s45, 0xc2fe0000
	s_mov_b32 s46, 0xc0c0500
	v_mbcnt_hi_u32_b32 v171, -1, v66
	v_mov_b32_e32 v172, 0x42fe0000
	s_branch .LBB0_39

.LBB0_39:
	s_cmpk_lt_i32 s27, 0x2c0
	s_cselect_b32 s18, 0, 0x2c0
	s_add_i32 s18, s18, s27
	s_cmpk_gt_i32 s18, 0x57f
	s_cselect_b64 s[20:21], -1, 0
	s_cmpk_lt_i32 s18, 0x580
	s_mul_hi_i32 s8, s18, 0x2e8ba2e9
	s_cselect_b64 s[22:23], -1, 0
	s_lshr_b32 s9, s8, 31
	s_ashr_i32 s26, s8, 5
	s_add_i32 s26, s26, s9
	s_mov_b64 s[8:9], -1
	s_and_b64 vcc, exec, s[22:23]
	s_cbranch_vccz .LBB0_41
	s_mul_i32 s8, s26, 0xb0
	s_sub_i32 s47, s18, s8
	s_mov_b64 s[8:9], 0

.LBB0_53:
	s_or_b64 exec, exec, s[8:9]
	s_waitcnt lgkmcnt(0)
	s_barrier
	v_mov_b32_e32 v66, s42
	ds_read_b32 v66, v66
	s_waitcnt lgkmcnt(0)
	v_cmp_lt_i32_e64 s[8:9], s43, v66
	v_readfirstlane_b32 s27, v66
	s_and_b64 vcc, exec, s[8:9]
	s_cbranch_vccnz .LBB0_60
	s_cmpk_lt_i32 s27, 0x2c0
	s_cselect_b32 s51, 0, 0x2c0
	s_add_i32 s51, s51, s27
	s_cmpk_lt_i32 s51, 0x580
	s_mul_hi_i32 s30, s51, 0x2e8ba2e9
	s_cselect_b64 s[28:29], -1, 0
	s_lshr_b32 s31, s30, 31
	s_ashr_i32 s53, s30, 5
	s_add_i32 s53, s53, s31
	s_mov_b64 s[30:31], -1
	s_and_b64 vcc, exec, s[28:29]
	s_cbranch_vccnz .LBB0_72
	s_andn2_b64 vcc, exec, s[30:31]
	s_movk_i32 s50, 0x1600
	s_cbranch_vccz .LBB0_73

.LBB0_700:
	s_andn2_b64 vcc, exec, s[4:5]
	s_cbranch_vccnz .LBB0_909
	s_mov_b64 s[18:19], s[0:1]
	s_load_dwordx2 s[14:15], s[18:19], 0x80
	v_mov_b32_e32 v130, v0
	s_mov_b32 s4, s33
	s_waitcnt lgkmcnt(0)
	s_mov_b32 s43, s85
	s_mov_b32 s55, s2
	s_sub_i32 s39, s43, 32
	v_readfirstlane_b32 s6, v130
	s_cmp_ge_i32 s55, s39
	s_mov_b64 s[4:5], -1
	s_cbranch_scc0 .LBB0_806
	v_readlane_b32 s8, v255, 29
	s_ashr_i32 s34, s6, 6
	v_readlane_b32 s9, v255, 30
	s_and_b64 s[4:5], s[8:9], exec
	s_cselect_b32 s4, 0x100, 0
	v_readlane_b32 s5, v255, 21
	s_add_u32 s16, s5, s4
	v_readlane_b32 s4, v255, 22
	v_and_b32_e32 v1, 63, v130
	s_addc_u32 s17, s4, 0
	s_andn2_b64 vcc, exec, s[8:9]
	s_movk_i32 s47, 0x2480
	s_movk_i32 s98, 0x2c0
	s_movk_i32 s99, 0x41f
	s_and_b64 s[4:5], s[8:9], exec
	s_cselect_b32 s98, 0x420, s98
	s_cselect_b32 s99, 0x57f, s99
	s_andn2_b32 s6, s6, 63
	v_or_b32_e32 v66, s6, v1
	v_cmp_eq_u32_e64 s[4:5], 0, v66
	s_barrier
	s_and_saveexec_b64 s[6:7], s[4:5]
	s_cbranch_execz .LBB0_707
	s_mov_b64 s[10:11], exec
	s_waitcnt vmcnt(0)
	v_mbcnt_lo_u32_b32 v2, s10, 0
	v_mbcnt_hi_u32_b32 v2, s11, v2
	v_cmp_eq_u32_e32 vcc, 0, v2
	s_and_saveexec_b64 s[8:9], vcc
	s_cbranch_execz .LBB0_706
	s_bcnt1_i32_b64 s10, s[10:11]
	v_mov_b32_e32 v3, s10
	global_atomic_add v3, v223, v3, s[16:17] offset:64 sc0
.LBB0_706:
	s_or_b64 exec, exec, s[8:9]
	s_waitcnt vmcnt(0)
	v_readfirstlane_b32 s8, v3
	s_nop 1
	v_add_u32_e32 v2, s8, v2
	v_readlane_b32 s8, v255, 23
	v_add_u32_e32 v2, s98, v2
	s_nop 0
	v_mov_b32_e32 v3, s8
	ds_write_b32 v3, v2
.LBB0_707:
	s_or_b64 exec, exec, s[6:7]
	v_readlane_b32 s6, v255, 23
	s_waitcnt lgkmcnt(0)
	s_barrier
	s_waitcnt vmcnt(0)
	v_mov_b32_e32 v2, s6
	ds_read_b32 v2, v2
	s_mov_b32 s6, s99
	s_waitcnt lgkmcnt(0)
	v_cmp_lt_i32_e32 vcc, s6, v2
	v_readfirstlane_b32 s23, v2
	s_cbranch_vccnz .LBB0_722
	s_mul_hi_i32 s6, s23, 0x2e8ba2e9
	s_lshr_b32 s7, s6, 31
	s_ashr_i32 s6, s6, 5
	s_add_i32 s9, s6, s7
	s_mul_i32 s6, s9, 0xb0
	s_lshl_b32 s7, s9, 1
	s_sub_i32 s8, s23, s6
	s_and_b32 s6, s9, 3
	s_and_b32 s7, s7, 4
	s_or_b32 s6, s6, s7
	s_lshl_b32 s6, s6, 3
	s_load_dwordx2 s[6:7], s[18:19], s6 offset:0x30
	s_ashr_i32 s9, s9, 2
	s_lshl_b32 s8, s8, 5
	s_mul_hi_i32 s10, s9, 0x2c00000
	s_mul_i32 s9, s9, 0x2c00000
	s_waitcnt lgkmcnt(0)
	s_add_u32 s11, s6, s9
	s_addc_u32 s10, s7, s10
	v_ashrrev_i32_e32 v67, 3, v66
	s_movk_i32 s6, 0x1600
	s_ashr_i32 s9, s8, 31
	v_mul_lo_u32 v2, v67, s6
	s_lshl_b64 s[6:7], s[8:9], 2
	s_add_u32 s6, s11, s6
	v_lshlrev_b32_e32 v3, 2, v1
	s_addc_u32 s7, s10, s7
	v_and_or_b32 v222, v3, 28, v2
	s_mov_b64 s[8:9], s[6:7]
	v_lshlrev_b64 v[132:133], 2, v[222:223]
	v_lshl_add_u64 v[2:3], s[8:9], 0, v[132:133]
	s_add_u32 s8, s6, 0x160000
	s_addc_u32 s9, s7, 0
	global_load_dwordx4 v[2:5], v[2:3], off nt
	v_lshlrev_b32_e32 v68, 3, v1
	v_lshl_add_u64 v[6:7], s[8:9], 0, v[132:133]
	s_add_u32 s8, s6, 0x2c0000
	s_addc_u32 s9, s7, 0
	global_load_dwordx4 v[6:9], v[6:7], off nt
	v_and_b32_e32 v70, 56, v68
	v_lshl_add_u64 v[10:11], s[8:9], 0, v[132:133]
	s_add_u32 s8, s6, 0x420000
	s_addc_u32 s9, s7, 0
	global_load_dwordx4 v[10:13], v[10:11], off nt
	v_add_u32_e32 v68, 64, v67
	v_lshl_add_u64 v[14:15], s[8:9], 0, v[132:133]
	s_add_u32 s8, s6, 0x580000
	s_addc_u32 s9, s7, 0
	global_load_dwordx4 v[14:17], v[14:15], off nt
	v_lshlrev_b32_e32 v69, 6, v68
	v_lshl_add_u64 v[18:19], s[8:9], 0, v[132:133]
	s_add_u32 s8, s6, 0x6e0000
	s_addc_u32 s9, s7, 0
	global_load_dwordx4 v[18:21], v[18:19], off nt
	v_ashrrev_i32_e32 v68, 1, v68
	v_lshl_add_u64 v[22:23], s[8:9], 0, v[132:133]
	s_add_u32 s8, s6, 0x840000
	s_addc_u32 s9, s7, 0
	global_load_dwordx4 v[22:25], v[22:23], off nt
	v_and_b32_e32 v68, 0xffffffc0, v68
	v_lshl_add_u64 v[26:27], s[8:9], 0, v[132:133]
	s_add_u32 s8, s6, 0x9a0000
	s_addc_u32 s9, s7, 0
	global_load_dwordx4 v[26:29], v[26:27], off nt
	v_add3_u32 v72, 0, v69, v68
	v_lshl_add_u64 v[30:31], s[8:9], 0, v[132:133]
	s_add_u32 s8, s6, 0xb00000
	s_addc_u32 s9, s7, 0
	global_load_dwordx4 v[30:33], v[30:31], off nt
	v_add_u32_e32 v68, 0x80, v67
	v_lshl_add_u64 v[34:35], s[8:9], 0, v[132:133]
	s_add_u32 s8, s6, 0xc60000
	s_addc_u32 s9, s7, 0
	global_load_dwordx4 v[34:37], v[34:35], off nt
	v_lshlrev_b32_e32 v69, 6, v68
	v_lshl_add_u64 v[38:39], s[8:9], 0, v[132:133]
	s_add_u32 s8, s6, 0xdc0000
	s_addc_u32 s9, s7, 0
	global_load_dwordx4 v[38:41], v[38:39], off nt
	v_ashrrev_i32_e32 v68, 1, v68
	v_lshl_add_u64 v[42:43], s[8:9], 0, v[132:133]
	s_add_u32 s8, s6, 0xf20000
	s_addc_u32 s9, s7, 0
	global_load_dwordx4 v[42:45], v[42:43], off nt
	v_and_b32_e32 v68, 0xffffffc0, v68
	v_lshl_add_u64 v[46:47], s[8:9], 0, v[132:133]
	s_add_u32 s8, s6, 0x1080000
	v_add3_u32 v73, 0, v69, v68
	v_add_u32_e32 v68, 0xc0, v67
	s_addc_u32 s9, s7, 0
	v_lshlrev_b32_e32 v69, 6, v68
	v_ashrrev_i32_e32 v68, 1, v68
	global_load_dwordx4 v[46:49], v[46:47], off nt
	v_and_b32_e32 v68, 0xffffffc0, v68
	v_lshl_add_u64 v[50:51], s[8:9], 0, v[132:133]
	s_add_u32 s8, s6, 0x11e0000
	v_add3_u32 v74, 0, v69, v68
	v_add_u32_e32 v68, 0x100, v67
	s_addc_u32 s9, s7, 0
	v_lshlrev_b32_e32 v69, 6, v68
	v_ashrrev_i32_e32 v68, 1, v68
	global_load_dwordx4 v[50:53], v[50:51], off nt
	v_and_b32_e32 v68, 0xffffffc0, v68
	v_lshl_add_u64 v[54:55], s[8:9], 0, v[132:133]
	s_add_u32 s8, s6, 0x1340000
	v_add3_u32 v75, 0, v69, v68
	v_add_u32_e32 v68, 0x140, v67
	s_addc_u32 s9, s7, 0
	v_lshlrev_b32_e32 v69, 6, v68
	v_ashrrev_i32_e32 v68, 1, v68
	s_add_u32 s6, s6, 0x14a0000
	v_and_b32_e32 v68, 0xffffffc0, v68
	global_load_dwordx4 v[54:57], v[54:55], off nt
	s_addc_u32 s7, s7, 0
	v_lshl_add_u64 v[58:59], s[8:9], 0, v[132:133]
	v_add3_u32 v76, 0, v69, v68
	v_add_u32_e32 v68, 0x180, v67
	global_load_dwordx4 v[58:61], v[58:59], off nt
	v_lshlrev_b32_e32 v69, 6, v68
	v_lshl_add_u64 v[62:63], s[6:7], 0, v[132:133]
	v_ashrrev_i32_e32 v68, 1, v68
	global_load_dwordx4 v[62:65], v[62:63], off nt
	v_and_b32_e32 v68, 0xffffffc0, v68
	v_add3_u32 v77, 0, v69, v68
	v_add_u32_e32 v68, 0x1c0, v67
	v_lshlrev_b32_e32 v69, 6, v68
	v_ashrrev_i32_e32 v68, 1, v68
	v_and_b32_e32 v68, 0xffffffc0, v68
	v_add3_u32 v78, 0, v69, v68
	v_add_u32_e32 v68, 0x200, v67
	v_lshlrev_b32_e32 v69, 6, v68
	v_ashrrev_i32_e32 v68, 1, v68
	v_and_b32_e32 v68, 0xffffffc0, v68
	v_add3_u32 v79, 0, v69, v68
	v_add_u32_e32 v68, 0x240, v67
	v_lshlrev_b32_e32 v69, 6, v68
	v_ashrrev_i32_e32 v68, 1, v68
	v_and_b32_e32 v68, 0xffffffc0, v68
	v_add3_u32 v80, 0, v69, v68
	v_add_u32_e32 v68, 0x280, v67
	v_lshlrev_b32_e32 v69, 6, v68
	v_ashrrev_i32_e32 v68, 1, v68
	v_and_b32_e32 v68, 0xffffffc0, v68
	v_add3_u32 v81, 0, v69, v68
	v_add_u32_e32 v68, 0x2c0, v67
	v_lshlrev_b32_e32 v69, 6, v68
	v_ashrrev_i32_e32 v68, 1, v68
	v_and_b32_e32 v68, 0xffffffc0, v68
	v_add3_u32 v82, 0, v69, v68
	v_add_u32_e32 v68, 0x300, v67
	v_lshlrev_b32_e32 v69, 6, v68
	v_ashrrev_i32_e32 v68, 1, v68
	v_and_b32_e32 v68, 0xffffffc0, v68
	v_add3_u32 v83, 0, v69, v68
	v_add_u32_e32 v68, 0x340, v67
	v_lshlrev_b32_e32 v69, 6, v68
	v_ashrrev_i32_e32 v68, 1, v68
	v_and_b32_e32 v68, 0xffffffc0, v68
	v_add3_u32 v84, 0, v69, v68
	v_add_u32_e32 v68, 0x380, v67
	v_lshlrev_b32_e32 v69, 6, v68
	v_ashrrev_i32_e32 v68, 1, v68
	v_and_b32_e32 v68, 0xffffffc0, v68
	v_add3_u32 v85, 0, v69, v68
	v_add_u32_e32 v68, 0x3c0, v67
	v_lshlrev_b32_e32 v69, 6, v68
	v_ashrrev_i32_e32 v68, 1, v68
	v_and_b32_e32 v68, 0xffffffc0, v68
	v_add3_u32 v86, 0, v69, v68
	v_add_u32_e32 v68, 0x400, v67
	v_lshlrev_b32_e32 v69, 6, v68
	v_ashrrev_i32_e32 v68, 1, v68
	v_and_b32_e32 v68, 0xffffffc0, v68
	v_add3_u32 v87, 0, v69, v68
	v_add_u32_e32 v68, 0x440, v67
	v_lshlrev_b32_e32 v69, 6, v68
	v_ashrrev_i32_e32 v68, 1, v68
	v_and_b32_e32 v68, 0xffffffc0, v68
	v_add3_u32 v88, 0, v69, v68
	v_add_u32_e32 v68, 0x480, v67
	v_lshlrev_b32_e32 v69, 6, v68
	v_ashrrev_i32_e32 v68, 1, v68
	v_and_b32_e32 v68, 0xffffffc0, v68
	v_add3_u32 v89, 0, v69, v68
	v_add_u32_e32 v68, 0x4c0, v67
	v_lshlrev_b32_e32 v69, 6, v68
	v_ashrrev_i32_e32 v68, 1, v68
	v_and_b32_e32 v68, 0xffffffc0, v68
	v_add3_u32 v90, 0, v69, v68
	v_add_u32_e32 v68, 0x500, v67
	v_lshlrev_b32_e32 v69, 6, v68
	v_ashrrev_i32_e32 v68, 1, v68
	v_and_b32_e32 v68, 0xffffffc0, v68
	v_add3_u32 v91, 0, v69, v68
	v_add_u32_e32 v68, 0x540, v67
	v_lshlrev_b32_e32 v69, 6, v68
	v_ashrrev_i32_e32 v68, 1, v68
	v_and_b32_e32 v68, 0xffffffc0, v68
	v_add3_u32 v92, 0, v69, v68
	v_add_u32_e32 v68, 0x580, v67
	v_lshlrev_b32_e32 v69, 6, v68
	v_ashrrev_i32_e32 v68, 1, v68
	v_and_b32_e32 v68, 0xffffffc0, v68
	v_add3_u32 v93, 0, v69, v68
	v_add_u32_e32 v68, 0x5c0, v67
	v_lshlrev_b32_e32 v69, 6, v68
	v_ashrrev_i32_e32 v68, 1, v68
	v_and_b32_e32 v68, 0xffffffc0, v68
	v_add3_u32 v94, 0, v69, v68
	v_add_u32_e32 v68, 0x600, v67
	v_lshlrev_b32_e32 v69, 6, v68
	v_ashrrev_i32_e32 v68, 1, v68
	v_and_b32_e32 v68, 0xffffffc0, v68
	v_add3_u32 v95, 0, v69, v68
	v_add_u32_e32 v68, 0x640, v67
	v_lshlrev_b32_e32 v69, 6, v68
	v_ashrrev_i32_e32 v68, 1, v68
	v_and_b32_e32 v68, 0xffffffc0, v68
	v_add3_u32 v96, 0, v69, v68
	v_add_u32_e32 v68, 0x680, v67
	v_lshlrev_b32_e32 v69, 6, v68
	v_ashrrev_i32_e32 v68, 1, v68
	v_and_b32_e32 v68, 0xffffffc0, v68
	v_add3_u32 v97, 0, v69, v68
	v_add_u32_e32 v68, 0x6c0, v67
	v_lshlrev_b32_e32 v69, 6, v68
	v_ashrrev_i32_e32 v68, 1, v68
	v_and_b32_e32 v68, 0xffffffc0, v68
	v_add3_u32 v98, 0, v69, v68
	v_add_u32_e32 v68, 0x700, v67
	v_lshlrev_b32_e32 v69, 6, v68
	v_ashrrev_i32_e32 v68, 1, v68
	v_and_b32_e32 v68, 0xffffffc0, v68
	v_add3_u32 v99, 0, v69, v68
	v_add_u32_e32 v68, 0x740, v67
	v_lshlrev_b32_e32 v69, 6, v68
	v_ashrrev_i32_e32 v68, 1, v68
	s_lshl_b32 s6, s34, 2
	v_and_b32_e32 v68, 0xffffffc0, v68
	s_andn2_b32 s6, s6, 63
	v_add3_u32 v100, 0, v69, v68
	v_add_u32_e32 v68, 0x780, v67
	s_add_i32 s6, s6, 0
	v_lshlrev_b32_e32 v69, 6, v68
	v_ashrrev_i32_e32 v68, 1, v68
	v_lshl_add_u32 v71, v67, 6, s6
	v_and_b32_e32 v68, 0xffffffc0, v68
	v_add_u32_e32 v67, 0x7c0, v67
	v_add3_u32 v101, 0, v69, v68
	v_lshlrev_b32_e32 v68, 6, v67
	v_ashrrev_i32_e32 v67, 1, v67
	v_and_b32_e32 v67, 0xffffffc0, v67
	v_add3_u32 v102, 0, v68, v67
	v_and_b32_e32 v131, 31, v130
	v_ashrrev_i32_e32 v67, 5, v66
	s_lshl_b32 s8, s34, 7
	v_readlane_b32 s9, v255, 24
	v_lshlrev_b32_e32 v68, 7, v67
	v_lshl_add_u32 v69, v67, 13, 0
	v_lshlrev_b32_e32 v67, 6, v67
	v_lshlrev_b32_e32 v104, 1, v131
	s_add_i32 s12, s9, s8
	v_add3_u32 v137, v69, v67, v104
	v_ashrrev_i32_e32 v69, 31, v68
	v_lshlrev_b32_e32 v103, 4, v1
	v_lshl_add_u32 v136, v131, 2, s9
	s_add_u32 s35, s14, 0x720000
	v_cmp_gt_u32_e64 s[8:9], 32, v66
	v_lshl_add_u64 v[66:67], s[14:15], 0, v[68:69]
	s_mov_b64 s[10:11], 0x800010
	v_cmp_gt_u32_e64 s[6:7], 8, v1
	s_addc_u32 s36, s15, 0
	v_lshl_add_u64 v[134:135], v[66:67], 0, s[10:11]
	v_add_u32_e32 v138, v71, v70
	v_add_u32_e32 v139, v72, v70
	v_add_u32_e32 v140, v73, v70
	v_add_u32_e32 v141, v74, v70
	v_add_u32_e32 v142, v75, v70
	v_add_u32_e32 v143, v76, v70
	v_add_u32_e32 v144, v77, v70
	v_add_u32_e32 v145, v78, v70
	v_add_u32_e32 v146, v79, v70
	v_add_u32_e32 v147, v80, v70
	v_add_u32_e32 v148, v81, v70
	v_add_u32_e32 v149, v82, v70
	v_add_u32_e32 v150, v83, v70
	v_add_u32_e32 v151, v84, v70
	v_add_u32_e32 v152, v85, v70
	v_add_u32_e32 v153, v86, v70
	v_add_u32_e32 v154, v87, v70
	v_add_u32_e32 v155, v88, v70
	v_add_u32_e32 v156, v89, v70
	v_add_u32_e32 v157, v90, v70
	v_add_u32_e32 v158, v91, v70
	v_add_u32_e32 v159, v92, v70
	v_add_u32_e32 v160, v93, v70
	v_add_u32_e32 v161, v94, v70
	v_add_u32_e32 v162, v95, v70
	v_add_u32_e32 v163, v96, v70
	v_add_u32_e32 v164, v97, v70
	v_add_u32_e32 v165, v98, v70
	v_add_u32_e32 v166, v99, v70
	v_add_u32_e32 v167, v100, v70
	v_add_u32_e32 v168, v101, v70
	v_add_u32_e32 v169, v102, v70
	v_add_u32_e32 v170, s12, v103
	s_branch .LBB0_710

.LBB0_713:
	s_or_b64 exec, exec, s[12:13]
	s_waitcnt vmcnt(0)
	v_readfirstlane_b32 s12, v172
	s_nop 1
	v_add_u32_e32 v171, s12, v171
	v_readlane_b32 s12, v255, 23
	v_add_u32_e32 v171, s98, v171
	s_nop 0
	v_mov_b32_e32 v172, s12
	ds_write_b32 v172, v171

.LBB0_716:
	s_or_b64 exec, exec, s[10:11]
	v_readlane_b32 s10, v255, 23
	s_waitcnt lgkmcnt(0)
	s_barrier
	s_nop 0
	v_mov_b32_e32 v66, s10
	ds_read_b32 v66, v66
	s_mov_b32 s10, s99
	s_waitcnt lgkmcnt(0)
	v_cmp_lt_i32_e64 s[10:11], s10, v66
	v_readfirstlane_b32 s23, v66
	s_and_b64 vcc, exec, s[10:11]
	s_cbranch_vccnz .LBB0_718
	s_mul_hi_i32 s12, s23, 0x2e8ba2e9
	s_lshr_b32 s13, s12, 31
	s_ashr_i32 s12, s12, 5
	s_add_i32 s29, s12, s13
	s_mul_i32 s12, s29, 0xb0
	s_lshl_b32 s13, s29, 1
	s_sub_i32 s28, s23, s12
	s_and_b32 s12, s29, 3
	s_and_b32 s13, s13, 4
	s_or_b32 s12, s12, s13
	s_lshl_b32 s12, s12, 3
	s_load_dwordx2 s[12:13], s[18:19], s12 offset:0x30
	s_ashr_i32 s29, s29, 2
	s_lshl_b32 s28, s28, 5
	s_mul_hi_i32 s44, s29, 0x2c00000
	s_mul_i32 s29, s29, 0x2c00000
	s_waitcnt lgkmcnt(0)
	s_add_u32 s45, s12, s29
	s_addc_u32 s44, s13, s44
	s_ashr_i32 s29, s28, 31
	s_lshl_b64 s[12:13], s[28:29], 2
	s_add_u32 s12, s45, s12
	s_addc_u32 s13, s44, s13
	s_mov_b64 s[28:29], s[12:13]
	s_nop 0
	v_lshl_add_u64 v[2:3], s[28:29], 0, v[132:133]
	s_add_u32 s28, s12, 0x160000
	s_addc_u32 s29, s13, 0
	global_load_dwordx4 v[2:5], v[2:3], off nt
	s_nop 0
	v_lshl_add_u64 v[6:7], s[28:29], 0, v[132:133]
	s_add_u32 s28, s12, 0x2c0000
	s_addc_u32 s29, s13, 0
	global_load_dwordx4 v[6:9], v[6:7], off nt
	s_nop 0
	v_lshl_add_u64 v[10:11], s[28:29], 0, v[132:133]
	s_add_u32 s28, s12, 0x420000
	s_addc_u32 s29, s13, 0
	global_load_dwordx4 v[10:13], v[10:11], off nt
	s_nop 0
	v_lshl_add_u64 v[14:15], s[28:29], 0, v[132:133]
	s_add_u32 s28, s12, 0x580000
	s_addc_u32 s29, s13, 0
	global_load_dwordx4 v[14:17], v[14:15], off nt
	s_nop 0
	v_lshl_add_u64 v[18:19], s[28:29], 0, v[132:133]
	s_add_u32 s28, s12, 0x6e0000
	s_addc_u32 s29, s13, 0
	global_load_dwordx4 v[18:21], v[18:19], off nt
	s_nop 0
	v_lshl_add_u64 v[22:23], s[28:29], 0, v[132:133]
	s_add_u32 s28, s12, 0x840000
	s_addc_u32 s29, s13, 0
	global_load_dwordx4 v[22:25], v[22:23], off nt
	s_nop 0
	v_lshl_add_u64 v[26:27], s[28:29], 0, v[132:133]
	s_add_u32 s28, s12, 0x9a0000
	s_addc_u32 s29, s13, 0
	global_load_dwordx4 v[26:29], v[26:27], off nt
	s_nop 0
	v_lshl_add_u64 v[30:31], s[28:29], 0, v[132:133]
	s_add_u32 s28, s12, 0xb00000
	s_addc_u32 s29, s13, 0
	global_load_dwordx4 v[30:33], v[30:31], off nt
	s_nop 0
	v_lshl_add_u64 v[34:35], s[28:29], 0, v[132:133]
	s_add_u32 s28, s12, 0xc60000
	s_addc_u32 s29, s13, 0
	global_load_dwordx4 v[34:37], v[34:35], off nt
	s_nop 0
	v_lshl_add_u64 v[38:39], s[28:29], 0, v[132:133]
	s_add_u32 s28, s12, 0xdc0000
	s_addc_u32 s29, s13, 0
	global_load_dwordx4 v[38:41], v[38:39], off nt
	s_nop 0
	v_lshl_add_u64 v[42:43], s[28:29], 0, v[132:133]
	s_add_u32 s28, s12, 0xf20000
	s_addc_u32 s29, s13, 0
	global_load_dwordx4 v[42:45], v[42:43], off nt
	s_nop 0
	v_lshl_add_u64 v[46:47], s[28:29], 0, v[132:133]
	s_add_u32 s28, s12, 0x1080000
	s_addc_u32 s29, s13, 0
	global_load_dwordx4 v[46:49], v[46:47], off nt
	s_nop 0
	v_lshl_add_u64 v[50:51], s[28:29], 0, v[132:133]
	s_add_u32 s28, s12, 0x11e0000
	s_addc_u32 s29, s13, 0
	global_load_dwordx4 v[50:53], v[50:51], off nt
	s_nop 0
	v_lshl_add_u64 v[54:55], s[28:29], 0, v[132:133]
	s_add_u32 s28, s12, 0x1340000
	s_addc_u32 s29, s13, 0
	s_add_u32 s12, s12, 0x14a0000
	global_load_dwordx4 v[54:57], v[54:55], off nt
	s_addc_u32 s13, s13, 0
	v_lshl_add_u64 v[58:59], s[28:29], 0, v[132:133]
	global_load_dwordx4 v[58:61], v[58:59], off nt
	s_nop 0
	v_lshl_add_u64 v[62:63], s[12:13], 0, v[132:133]
	global_load_dwordx4 v[62:65], v[62:63], off nt

.LBB0_722:
	v_readlane_b32 s8, v255, 29
	v_readlane_b32 s9, v255, 30
	s_movk_i32 s47, 0x2480
	s_and_b64 s[8:9], s[8:9], exec
	s_cselect_b32 s47, 0xf00, s47
	s_barrier
